# per-tile accumulator zeroing done by 7 v_mfma_f32_32x32x16_bf16 on zero operands (16 regs each) plus 8 v_mov_b64, instead of 64 v_mov_b64
# baseline (speedup 1.0000x reference)
;     ...
;         if (!has_next) break;
; #pragma unroll
;         for (int a = 0; a < 2; ++a)
; #pragma unroll
;             for (int b = 0; b < 2; ++b)
; #pragma unroll
;                 for (int m = 0; m < 4; ++m)
; #pragma unroll
;                     for (int n = 0; n < 2; ++n) acc[a][b][m][n] = (f32x4){0.f, 0.f, 0.f, 0.f};
;         cur = nxt; cA = nA; cB = nB; ++ui;
.LBB0_82:
	s_andn2_b64 vcc, exec, s[24:25]
	s_waitcnt lgkmcnt(0)
	s_cbranch_vccnz .Lzskip_0
	s_add_u32 s14, s4, 0x100
	v_mov_b64_e32 v[0:1], 0
	v_mov_b64_e32 v[2:3], 0
	v_mov_b64_e32 v[4:5], 0
	v_mov_b64_e32 v[6:7], 0
	v_mov_b64_e32 v[8:9], 0
	v_mov_b64_e32 v[10:11], 0
	v_mov_b64_e32 v[12:13], 0
	v_mov_b64_e32 v[14:15], 0
	s_nop 1
	v_mfma_f32_32x32x16_bf16 v[16:31], v[0:3], v[0:3], 0
	v_mfma_f32_32x32x16_bf16 v[32:47], v[0:3], v[0:3], 0
	v_mfma_f32_32x32x16_bf16 v[48:63], v[0:3], v[0:3], 0
	v_mfma_f32_32x32x16_bf16 v[64:79], v[0:3], v[0:3], 0
	v_mfma_f32_32x32x16_bf16 v[80:95], v[0:3], v[0:3], 0
	v_mfma_f32_32x32x16_bf16 v[96:111], v[0:3], v[0:3], 0
	v_mfma_f32_32x32x16_bf16 v[112:127], v[0:3], v[0:3], 0
	s_addc_u32 s15, s5, 0
	s_mov_b32 s8, 0
	s_mov_b64 s[58:59], 0x80

;     ...
;         if (!has_next) break;
; #pragma unroll
;         for (int a = 0; a < 2; ++a)
; #pragma unroll
;             for (int b = 0; b < 2; ++b)
; #pragma unroll
;                 for (int m = 0; m < 4; ++m)
; #pragma unroll
;                     for (int n = 0; n < 2; ++n) acc[a][b][m][n] = (f32x4){0.f, 0.f, 0.f, 0.f};
;         cur = nxt; cA = nA; cB = nB; ++ui;
.LBB0_131:
	s_andn2_b64 vcc, exec, s[28:29]
	s_cbranch_vccnz .Lzskip_1
	s_add_u32 s7, s2, 0x100
	v_mov_b64_e32 v[0:1], 0
	v_mov_b64_e32 v[2:3], 0
	v_mov_b64_e32 v[4:5], 0
	v_mov_b64_e32 v[6:7], 0
	v_mov_b64_e32 v[8:9], 0
	v_mov_b64_e32 v[10:11], 0
	v_mov_b64_e32 v[12:13], 0
	v_mov_b64_e32 v[14:15], 0
	s_nop 1
	v_mfma_f32_32x32x16_bf16 v[16:31], v[0:3], v[0:3], 0
	v_mfma_f32_32x32x16_bf16 v[32:47], v[0:3], v[0:3], 0
	v_mfma_f32_32x32x16_bf16 v[48:63], v[0:3], v[0:3], 0
	v_mfma_f32_32x32x16_bf16 v[64:79], v[0:3], v[0:3], 0
	v_mfma_f32_32x32x16_bf16 v[80:95], v[0:3], v[0:3], 0
	v_mfma_f32_32x32x16_bf16 v[96:111], v[0:3], v[0:3], 0
	v_mfma_f32_32x32x16_bf16 v[112:127], v[0:3], v[0:3], 0
	v_mov_b64_e32 v[212:213], 0x77f
	v_mov_b64_e32 v[154:155], 0x780
	s_addc_u32 s8, s3, 0
	s_mov_b32 s4, 0
	s_mov_b64 s[58:59], 0x80

;     ...
;         const char* nA = has_next ? (const char*)g.A + (size_t)nxt.pm * tstepA + (size_t)nxt.pn * APN : cA; const char* nB = has_next ? (const char*)g.Bt + (size_t)nxt.pn * tstepB : cB;
;     ...
;         if (!has_next) break;
; #pragma unroll
;         for (int a = 0; a < 2; ++a)
; #pragma unroll
;             for (int b = 0; b < 2; ++b)
; #pragma unroll
;                 for (int m = 0; m < 4; ++m)
; #pragma unroll
;                     for (int n = 0; n < 2; ++n) acc[a][b][m][n] = (f32x4){0.f, 0.f, 0.f, 0.f};
;         cur = nxt; cA = nA; cB = nB; ++ui;
.LBB0_204:
	s_ashr_i32 s17, s16, 31
	s_lshl_b64 s[22:23], s[16:17], 19
	v_readlane_b32 s52, v254, 28
	v_readlane_b32 s53, v254, 29
	s_add_u32 s22, s52, s22
	s_addc_u32 s23, s53, s23
	s_andn2_b64 vcc, exec, s[8:9]
	s_cbranch_vccnz .Lzskip_2
	s_and_b64 s[12:13], s[12:13], exec
	s_cselect_b32 s17, s23, s29
	s_cselect_b32 s52, s22, s28
	s_add_u32 s12, s28, 0x40080
	s_addc_u32 s13, s29, 0
	s_add_u32 s28, s26, 0x100
	v_mov_b64_e32 v[0:1], 0
	v_mov_b64_e32 v[2:3], 0
	v_mov_b64_e32 v[4:5], 0
	v_mov_b64_e32 v[6:7], 0
	v_mov_b64_e32 v[8:9], 0
	v_mov_b64_e32 v[10:11], 0
	v_mov_b64_e32 v[12:13], 0
	v_mov_b64_e32 v[14:15], 0
	s_nop 1
	v_mfma_f32_32x32x16_bf16 v[16:31], v[0:3], v[0:3], 0
	v_mfma_f32_32x32x16_bf16 v[32:47], v[0:3], v[0:3], 0
	v_mfma_f32_32x32x16_bf16 v[48:63], v[0:3], v[0:3], 0
	v_mfma_f32_32x32x16_bf16 v[64:79], v[0:3], v[0:3], 0
	v_mfma_f32_32x32x16_bf16 v[80:95], v[0:3], v[0:3], 0
	v_mfma_f32_32x32x16_bf16 v[96:111], v[0:3], v[0:3], 0
	v_mfma_f32_32x32x16_bf16 v[112:127], v[0:3], v[0:3], 0
	s_addc_u32 s29, s27, 0
	s_mov_b32 s26, 0
	s_mov_b64 s[58:59], 0x80

;     ...
;         if (!has_next) break;
; #pragma unroll
;         for (int a = 0; a < 2; ++a)
; #pragma unroll
;             for (int b = 0; b < 2; ++b)
; #pragma unroll
;                 for (int m = 0; m < 4; ++m)
; #pragma unroll
;                     for (int n = 0; n < 2; ++n) acc[a][b][m][n] = (f32x4){0.f, 0.f, 0.f, 0.f};
;         cur = nxt; cA = nA; cB = nB; ++ui;
.LBB0_312:
	s_andn2_b64 vcc, exec, s[22:23]
	s_cbranch_vccnz .Lzskip_5
	s_add_u32 s48, s2, 0x100
	v_mov_b64_e32 v[0:1], 0
	v_mov_b64_e32 v[2:3], 0
	v_mov_b64_e32 v[4:5], 0
	v_mov_b64_e32 v[6:7], 0
	v_mov_b64_e32 v[8:9], 0
	v_mov_b64_e32 v[10:11], 0
	v_mov_b64_e32 v[12:13], 0
	v_mov_b64_e32 v[14:15], 0
	s_nop 1
	v_mfma_f32_32x32x16_bf16 v[16:31], v[0:3], v[0:3], 0
	v_mfma_f32_32x32x16_bf16 v[32:47], v[0:3], v[0:3], 0
	v_mfma_f32_32x32x16_bf16 v[48:63], v[0:3], v[0:3], 0
	v_mfma_f32_32x32x16_bf16 v[64:79], v[0:3], v[0:3], 0
	v_mfma_f32_32x32x16_bf16 v[80:95], v[0:3], v[0:3], 0
	v_mfma_f32_32x32x16_bf16 v[96:111], v[0:3], v[0:3], 0
	v_mfma_f32_32x32x16_bf16 v[112:127], v[0:3], v[0:3], 0
	s_addc_u32 s49, s3, 0
	s_mov_b32 s4, 0
	s_mov_b64 s[56:57], 0x80

;     ...
;         const char* nA = has_next ? (const char*)g.A + (size_t)nxt.pm * tstepA + (size_t)nxt.pn * APN : cA; const char* nB = has_next ? (const char*)g.Bt + (size_t)nxt.pn * tstepB : cB;
;     ...
;         if (!has_next) break;
; #pragma unroll
;         for (int a = 0; a < 2; ++a)
; #pragma unroll
;             for (int b = 0; b < 2; ++b)
; #pragma unroll
;                 for (int m = 0; m < 4; ++m)
; #pragma unroll
;                     for (int n = 0; n < 2; ++n) acc[a][b][m][n] = (f32x4){0.f, 0.f, 0.f, 0.f};
;         cur = nxt; cA = nA; cB = nB; ++ui;
.LBB0_551:
	s_ashr_i32 s21, s20, 31
	s_lshl_b64 s[24:25], s[20:21], 19
	v_readlane_b32 s52, v254, 28
	v_readlane_b32 s53, v254, 29
	s_add_u32 s24, s52, s24
	s_addc_u32 s25, s53, s25
	s_andn2_b64 vcc, exec, s[8:9]
	s_waitcnt lgkmcnt(0)
	s_cbranch_vccnz .Lzskip_7
	s_and_b64 s[12:13], s[12:13], exec
	s_cselect_b32 s21, s25, s29
	s_cselect_b32 s51, s24, s28
	s_add_u32 s12, s28, 0x40080
	s_addc_u32 s13, s29, 0
	s_add_u32 s28, s26, 0x100
	v_mov_b64_e32 v[0:1], 0
	v_mov_b64_e32 v[2:3], 0
	v_mov_b64_e32 v[4:5], 0
	v_mov_b64_e32 v[6:7], 0
	v_mov_b64_e32 v[8:9], 0
	v_mov_b64_e32 v[10:11], 0
	v_mov_b64_e32 v[12:13], 0
	v_mov_b64_e32 v[14:15], 0
	s_nop 1
	v_mfma_f32_32x32x16_bf16 v[16:31], v[0:3], v[0:3], 0
	v_mfma_f32_32x32x16_bf16 v[32:47], v[0:3], v[0:3], 0
	v_mfma_f32_32x32x16_bf16 v[48:63], v[0:3], v[0:3], 0
	v_mfma_f32_32x32x16_bf16 v[64:79], v[0:3], v[0:3], 0
	v_mfma_f32_32x32x16_bf16 v[80:95], v[0:3], v[0:3], 0
	v_mfma_f32_32x32x16_bf16 v[96:111], v[0:3], v[0:3], 0
	v_mfma_f32_32x32x16_bf16 v[112:127], v[0:3], v[0:3], 0
	s_addc_u32 s29, s27, 0
	s_mov_b32 s26, 0
	s_mov_b64 s[58:59], 0x80
